# attention K/V staging via direct HBM-to-LDS loads (global_load_lds_dwordx4 with per-lane gathered source addresses for the swizzled K / sub-tiled V images) instead of VGPR staging plus ds_write; 24 st
# speedup vs baseline: 1.0294x; 1.0260x over previous
; __device__ __forceinline__ int v_st(int k, int c) { const int kk = (k & ~0xC) | ((k & 4) << 1) | ((k & 8) >> 1); return ((kk >> 3) * 4 + (c >> 5)) * 512 + ((kk & 7) * 32 + (c & 31)) * 2; }
; __device__ __forceinline__ int v_rd_base(int lane) { return ((lane & 3) << 3) | (((lane >> 2) & 3) << 6) | (((lane >> 4) & 1) << 5) | (((lane >> 5) & 1) << 8); }
; __device__ __forceinline__ void attn2_block(const Block2& B, char* lds) {
;     int tid_l = threadIdx.x; asm volatile("" : "+v"(tid_l)); const int tid = tid_l, wid = __builtin_amdgcn_readfirstlane(tid >> 6), lane = tid & 63, r32 = lane & 31, hi = lane >> 5;
;     const int pr = wid & 3, kh = wid >> 2;
;     const int NT = (B.P0 + 127) / KVBLK + 1;
;     const int qlo = B.P0 + pr * 32;
;     ...
;     char* V_lds = lds; char* K_lds = lds + A2_K;
;     char* xp_own = lds + A2_XP + wid * 2048 + lane * 16; const char* xp_oth = lds + A2_XP + (wid ^ 4) * 2048 + lane * 16;
;     float* xm = (float*)(lds + A2_XM); float* al_l = (float*)(lds + A2_AL) + wid * 32; float* li_l = al_l;
;     const int sr = tid >> 4, sc = (tid & 15) * 8, vst0 = v_st(sr, sc), vst1 = v_st(32 + sr, sc), kws = KSWZ(sr, sc * 2);
;     const int vb0 = (int)(uintptr_t)V_lds + v_rd_base(lane);
;     bf16x8 st_k0, st_k1, st_a0, st_a1, st_b0, st_b1;
;     const unsigned toff = (unsigned)(sr * D + sc) * 2u;
;     ...
;     char* qf = lds + A2_Q + pr * 7168 + lane * 16;
;     const bf16x8 q0 = load8<bf16>(B.Q + (size_t)(pr * 32 + r32) * D + hi * 8);
;     if (kh == 0) {
; #pragma unroll
;         for (int d0 = 1; d0 < 8; ++d0) *(bf16x8*)(qf + (d0 - 1) * 1024) = load8<bf16>(B.Q + (size_t)(pr * 32 + r32) * D + d0 * 16 + hi * 8); }
; __device__ __forceinline__ void attn2_phase(const Args& a, int l, int vcu, int G, unsigned char* ldsg) {
;     ...
;         for (int k = 0; k < 4; ++k) { const int c = k >> 1, qb = (k & 1) ? 63 - x : x, iqk = bh * 2 + c;
;             att::Block2 B;
;             B.Q = (const att::bf16*)(a.ws + WS_QH) + ((size_t)iqk * SEQ + (size_t)qb * 128) * 128;
;             B.K = (const att::bf16*)(a.ws + WS_KH) + (size_t)iqk * SEQ * 128;
;             B.V0 = (const att::bf16*)(a.ws + WS_VH) + (size_t)(bh * 2) * SEQ * 128; B.V1 = B.V0 + (size_t)SEQ * 128;
;             B.O0 = (att::bf16*)(a.ws + WS_OH) + ((size_t)(iqk * 2) * SEQ + (size_t)qb * 128) * 128; B.O1 = B.O0 + (size_t)SEQ * 128;
;             B.P0 = qb * 128; B.desc = k & 1;
.LBB0_342:
	s_lshr_b32 s2, s82, 1
	s_or_b32 s14, s2, s6
	s_and_b32 s3, s82, 1
	s_ashr_i32 s15, s14, 31
	s_cmp_eq_u32 s3, 0
	s_cselect_b64 s[46:47], -1, 0
	s_and_b64 s[2:3], s[46:47], exec
	s_cselect_b32 s91, s80, s78
	s_lshl_b64 s[2:3], s[14:15], 21
	s_lshl_b32 s15, s91, 8
	s_add_u32 s4, s54, s15
	s_addc_u32 s5, s56, 0
	v_mov_b32_e32 v208, v192
	s_add_u32 s4, s4, s2
	s_addc_u32 s5, s5, s3
	v_readfirstlane_b32 s50, v208
	s_ashr_i32 s89, s50, 6
	s_lshl_b32 s100, s89, 10
	v_lshrrev_b32_e32 v252, 4, v207
	v_lshl_add_u32 v252, s89, 2, v252
	v_and_b32_e32 v253, 7, v252
	v_and_b32_e32 v250, 15, v207
	v_xor_b32_e32 v250, v250, v253
	v_lshlrev_b32_e32 v250, 4, v250
	v_lshl_add_u32 v250, v252, 8, v250
	v_bfe_u32 v252, v207, 2, 2
	v_bfe_u32 v253, v207, 4, 1
	v_lshl_or_b32 v252, v253, 3, v252
	s_bfe_u32 s101, s89, 0x10001
	s_lshl_b32 s101, s101, 2
	v_or_b32_e32 v252, s101, v252
	s_lshr_b32 s101, s89, 2
	s_lshl_b32 s101, s101, 4
	v_or_b32_e32 v252, s101, v252
	v_lshlrev_b32_e32 v251, 8, v252
	s_and_b32 s101, s89, 1
	s_lshl_b32 s101, s101, 1
	v_lshrrev_b32_e32 v252, 5, v207
	v_add_u32_e32 v252, s101, v252
	v_lshlrev_b32_e32 v252, 6, v252
	v_and_b32_e32 v253, 3, v207
	v_lshl_add_u32 v252, v253, 4, v252
	v_add_u32_e32 v251, v251, v252
	s_and_b32 s83, s89, 3
	v_and_b32_e32 v189, 31, v208
	s_lshl_b32 s38, s83, 5
	v_or_b32_e32 v0, s38, v189
	v_bfe_u32 v209, v208, 5, 1
	v_lshlrev_b32_e32 v194, 8, v0
	v_lshl_add_u64 v[0:1], s[4:5], 0, v[194:195]
	v_lshlrev_b32_e32 v196, 4, v209
	v_mov_b32_e32 v197, v195
	v_lshl_add_u64 v[0:1], v[0:1], 0, v[196:197]
	global_load_dwordx4 v[144:147], v[0:1], off
	s_mul_i32 s4, s83, 0x1c00
	s_add_i32 s4, s4, 0
	s_add_i32 s4, s4, 0x20c00
	s_cmpk_lt_u32 s50, 0x100
	v_and_b32_e32 v33, 63, v208
	s_cselect_b64 s[16:17], -1, 0
	s_cmpk_gt_u32 s50, 0xff
	v_lshlrev_b32_e32 v32, 4, v33
	s_cselect_b64 s[48:49], -1, 0
	s_and_b64 vcc, exec, s[48:49]
	v_add_u32_e32 v210, s4, v32
	s_cbranch_vccnz .LBB0_344
	global_load_dwordx4 v[2:5], v[0:1], off offset:32
	global_load_dwordx4 v[6:9], v[0:1], off offset:64
	global_load_dwordx4 v[10:13], v[0:1], off offset:96
	global_load_dwordx4 v[14:17], v[0:1], off offset:128
	global_load_dwordx4 v[18:21], v[0:1], off offset:160
	global_load_dwordx4 v[22:25], v[0:1], off offset:192
	global_load_dwordx4 v[26:29], v[0:1], off offset:224
	s_waitcnt vmcnt(6)
	ds_write_b128 v210, v[2:5]
	s_waitcnt vmcnt(5)
	ds_write_b128 v210, v[6:9] offset:1024
	s_waitcnt vmcnt(4)
	ds_write_b128 v210, v[10:13] offset:2048
	s_waitcnt vmcnt(3)
	ds_write_b128 v210, v[14:17] offset:3072
	s_waitcnt vmcnt(2)
	ds_write_b128 v210, v[18:21] offset:4096
	s_waitcnt vmcnt(1)
	ds_write_b128 v210, v[22:25] offset:5120
	s_waitcnt vmcnt(0)
	ds_write_b128 v210, v[26:29] offset:6144
; #define SBAR() __builtin_amdgcn_sched_barrier(0)
; #define A2_SLOAD_K(t) do { const int k0_ = A2_TILE(t) * KVBLK; st_k0 = A2_LD(B.K, k0_, 0); st_k1 = A2_LD(B.K, k0_, 32); } while (0)
; #define A2_SLOAD_V(t) do { const int k0_ = A2_TILE(t) * KVBLK; st_a0 = A2_LD(B.V0, k0_, 0); st_a1 = A2_LD(B.V0, k0_, 32); st_b0 = A2_LD(B.V1, k0_, 0); st_b1 = A2_LD(B.V1, k0_, 32); } while (0)
; #define A2_SWRITE_K(bf) do { *(bf16x8*)(K_lds + (bf) * SHM_K + kws) = st_k0; *(bf16x8*)(K_lds + (bf) * SHM_K + kws + 32 * 256) = st_k1; } while (0)
; #define A2_VMW() asm volatile("s_waitcnt vmcnt(0)" ::: "memory")
; __device__ __forceinline__ void attn2_block(const Block2& B, char* lds) {
;     ...
;     A2_SLOAD_K(0); A2_VMW(); A2_SWRITE_K(0); SBAR(); A2_SLOAD_K(1); A2_SLOAD_V(0);
;     __syncthreads();
;     float l_reg = 0.f; f32x16 o[4] = {};
;     f32x16 p; bf16x8 own0 = {}, own1 = {}, oth0, oth1;
;     constexpr float C2 = 1.4426950408889634f * SCALE;
;     ...
;     float m_cur, mn_p, alpha_p = 1.f, pmax_own;
;     qkt_half<0>(p, K_lds, r32, hi, kh, qf, q0); SBAR(); A3_MASKMAX(0, 0);
;     __syncthreads();
;     m_cur = fmaxf(fmaxf(pmax_own, xm[(wid ^ 4) * 32 + r32]), -1e30f); mn_p = m_cur;
.LBB0_344:
	s_add_u32 s4, s58, s2
	s_addc_u32 s5, s60, s3
	s_lshr_b32 s84, s91, 6
	s_or_b32 s85, s84, 1
	s_lshl_b32 s51, s85, 6
	s_or_b32 s86, s38, s91
	s_lshl_b32 s88, s89, 5
	s_sub_i32 s38, s51, 64
	s_and_b64 s[2:3], s[46:47], exec
	s_cselect_b32 s96, 0, s38
	s_lshl_b32 s90, s96, 8
	v_lshlrev_b32_e32 v0, 3, v208
	s_add_u32 s2, s4, s90
	v_ashrrev_i32_e32 v39, 4, v208
	v_and_b32_e32 v41, 0x78, v0
	s_addc_u32 s3, s5, 0
	s_or_b32 s38, s96, 32
	v_lshlrev_b32_e32 v40, 1, v41
	v_lshlrev_b32_e32 v8, 8, v39
	s_lshl_b64 s[92:93], s[38:39], 8
	v_or_b32_e32 v194, v40, v8
	s_add_u32 s52, s4, s92
	s_addc_u32 s53, s5, s93
	global_load_dwordx4 v[0:3], v194, s[2:3]
	global_load_dwordx4 v[4:7], v194, s[52:53]
	v_and_b32_e32 v9, 0x70, v208
	s_waitcnt vmcnt(0)
	v_bitop3_b32 v42, v40, v8, v9 bitop3:0xde
	v_add_u32_e32 v8, s69, v42
	s_waitcnt vmcnt(1)
	ds_write_b128 v8, v[0:3]
	s_waitcnt vmcnt(0)
	ds_write_b128 v8, v[4:7] offset:8192
	s_and_b64 s[2:3], s[46:47], exec
	s_cselect_b32 s87, 64, s51
	s_lshl_b32 s38, s87, 8
	s_add_u32 s2, s4, s38
	s_addc_u32 s3, s5, 0
	s_or_b32 s52, s38, 0x2000
	s_add_u32 s94, s4, s52
	s_addc_u32 s95, s5, 0
	global_load_dwordx4 v[148:151], v194, s[2:3]
	global_load_dwordx4 v[152:155], v194, s[94:95]
	s_add_u32 s2, s8, s90
	s_addc_u32 s3, s9, 0
	s_add_u32 s94, s8, s92
	s_addc_u32 s95, s9, s93
	global_load_dwordx4 v[16:19], v194, s[2:3]
	global_load_dwordx4 v[20:23], v194, s[94:95]
	s_add_u32 s2, s12, s90
	s_addc_u32 s3, s13, 0
	s_add_u32 s92, s12, s92
	s_addc_u32 s93, s13, s93
	global_load_dwordx4 v[24:27], v194, s[2:3]
	global_load_dwordx4 v[28:31], v194, s[92:93]
	s_lshl_b32 s2, s50, 5
	s_and_b32 s90, s2, 0xffffe000
	v_lshlrev_b32_e32 v4, 4, v189
	s_add_i32 s2, s69, s90
	v_bitop3_b32 v35, v196, v4, s68 bitop3:0x78
	v_lshlrev_b32_e32 v34, 8, v189
	v_add_u32_e32 v0, s2, v35
	v_add_u32_e32 v211, v0, v34
	s_waitcnt lgkmcnt(0)
	s_barrier
	ds_read_b128 v[0:3], v211
	ds_read_b128 v[52:55], v210
	v_and_b32_e32 v38, 0x70, v4
	v_bitop3_b32 v36, v196, v38, 32 bitop3:0x36
	v_add_u32_e32 v4, s2, v36
	v_add_u32_e32 v212, v4, v34
	ds_read_b128 v[44:47], v211 offset:128
	ds_read_b128 v[48:51], v212
	s_waitcnt lgkmcnt(3)
	v_mfma_f32_32x32x16_bf16 v[0:15], v[0:3], v[144:147], 0
	v_bitop3_b32 v37, v196, v38, 64 bitop3:0x36
	v_add_u32_e32 v43, s2, v37
	v_add_u32_e32 v213, v43, v34
	ds_read_b128 v[56:59], v210 offset:1024
	ds_read_b128 v[60:63], v212 offset:128
	v_bitop3_b32 v38, v196, v38, s70 bitop3:0x36
	v_add_u32_e32 v43, s2, v38
	v_add_u32_e32 v214, v43, v34
	s_waitcnt lgkmcnt(2)
	v_mfma_f32_32x32x16_bf16 v[0:15], v[48:51], v[52:55], v[0:15]
	ds_read_b128 v[48:51], v213
	ds_read_b128 v[52:55], v213 offset:128
	s_mov_b32 s53, s39
	s_waitcnt lgkmcnt(1)
	v_mfma_f32_32x32x16_bf16 v[0:15], v[48:51], v[56:59], v[0:15]
	ds_read_b128 v[48:51], v214
	ds_read_b128 v[56:59], v210 offset:2048
	ds_read_b128 v[64:67], v210 offset:3072
	ds_read_b128 v[68:71], v214 offset:128
	s_waitcnt lgkmcnt(2)
	v_mfma_f32_32x32x16_bf16 v[0:15], v[48:51], v[56:59], v[0:15]
	s_waitcnt lgkmcnt(1)
	v_mfma_f32_32x32x16_bf16 v[0:15], v[44:47], v[64:67], v[0:15]
	ds_read_b128 v[44:47], v210 offset:4096
	ds_read_b128 v[48:51], v210 offset:5120
	s_waitcnt lgkmcnt(1)
	v_mfma_f32_32x32x16_bf16 v[0:15], v[60:63], v[44:47], v[0:15]
	ds_read_b128 v[44:47], v210 offset:6144
	s_waitcnt lgkmcnt(1)
	v_mfma_f32_32x32x16_bf16 v[0:15], v[52:55], v[48:51], v[0:15]
	s_waitcnt lgkmcnt(0)
	v_mfma_f32_32x32x16_bf16 v[0:15], v[68:71], v[44:47], v[0:15]
	s_cmp_le_u32 s96, s86
	s_cselect_b64 vcc, -1, 0
	s_nop 9
	v_cndmask_b32_e32 v43, v204, v13, vcc
	v_cndmask_b32_e32 v13, v204, v14, vcc
	v_cndmask_b32_e32 v14, v204, v10, vcc
	v_cndmask_b32_e32 v10, v204, v11, vcc
	v_cndmask_b32_e32 v11, v204, v8, vcc
	v_cndmask_b32_e32 v8, v204, v9, vcc
	v_cndmask_b32_e32 v9, v204, v5, vcc
	v_cndmask_b32_e32 v5, v204, v6, vcc
	v_cndmask_b32_e32 v6, v204, v1, vcc
	v_cndmask_b32_e32 v2, v204, v2, vcc
	v_cndmask_b32_e32 v1, v204, v3, vcc
	v_cndmask_b32_e32 v44, v204, v12, vcc
	v_cndmask_b32_e32 v12, v204, v15, vcc
	v_cndmask_b32_e32 v15, v204, v4, vcc
	v_cndmask_b32_e32 v4, v204, v7, vcc
	v_cndmask_b32_e32 v7, v204, v0, vcc
	v_max_f32_e32 v0, v1, v1
	v_max_f32_e32 v3, v2, v2
	v_max_f32_e32 v0, v3, v0
	v_max_f32_e32 v3, v4, v4
	v_max_f32_e32 v45, v5, v5
	v_max_f32_e32 v3, v45, v3
	v_max_f32_e32 v45, v8, v8
	v_max_f32_e32 v46, v11, v11
	v_max_f32_e32 v45, v46, v45
	v_max_f32_e32 v46, v10, v10
	v_max_f32_e32 v47, v14, v14
	v_max_f32_e32 v46, v47, v46
	v_max_f32_e32 v47, v12, v12
	v_max_f32_e32 v48, v13, v13
	v_max_f32_e32 v47, v48, v47
	v_max3_f32 v47, v44, v43, v47
	v_max3_f32 v0, v7, v6, v0
	v_max3_f32 v3, v15, v9, v3
	v_max3_f32 v45, v45, v46, v47
	v_max3_f32 v0, v0, v3, v45
	v_mov_b32_e32 v3, v0
	s_nop 1
	v_permlane32_swap_b32_e32 v0, v3
	v_max_f32_e32 v3, v3, v3
	v_max_f32_e32 v0, v0, v0
	v_max_f32_e32 v0, v0, v3
	v_cmp_gt_u32_e64 s[2:3], 32, v33
	s_and_saveexec_b64 s[50:51], s[2:3]
	s_lshl_b32 s92, s88, 2
	s_add_i32 s92, s92, 0
	v_lshl_add_u32 v3, v189, 2, s92
	v_add_u32_e32 v3, 0x20000, v3
	ds_write_b32 v3, v0
	s_or_b64 exec, exec, s[50:51]
	v_and_b32_e32 v3, 0xfffff0, v39
	v_lshlrev_b32_e32 v45, 1, v39
	v_and_or_b32 v3, v45, 8, v3
	v_lshrrev_b32_e32 v45, 1, v39
	v_lshrrev_b32_e32 v3, 1, v3
	v_lshrrev_b32_e32 v41, 5, v41
	v_and_b32_e32 v46, 3, v39
	v_or_b32_e32 v3, v3, v41
	v_and_or_b32 v45, v45, 4, v46
	v_lshlrev_b32_e32 v3, 9, v3
	v_lshlrev_b32_e32 v45, 6, v45
	v_and_b32_e32 v40, 48, v40
	v_or3_b32 v46, v3, v45, v40
	v_add_u32_e32 v3, 32, v39
	v_and_b32_e32 v39, 0xfffff0, v3
	v_lshlrev_b32_e32 v3, 1, v3
	v_and_or_b32 v3, v3, 8, v39
	s_xor_b32 s92, s89, 4
	v_lshrrev_b32_e32 v3, 1, v3
	v_or_b32_e32 v3, v3, v41
	s_lshl_b32 s50, s92, 7
	v_lshlrev_b32_e32 v3, 9, v3
	s_add_i32 s50, s50, 0
	v_or3_b32 v39, v3, v45, v40
	v_lshl_add_u32 v3, v189, 2, s50
	v_add_u32_e32 v197, 0x20000, v3
	s_waitcnt lgkmcnt(0)
	s_barrier
	ds_read_b32 v3, v197
	v_add_u32_e32 v96, 0, v42
	v_add_u32_e32 v215, 0x14000, v96
	v_add_u32_e32 v216, 0, v46
	v_add_u32_e32 v217, 0, v39
	v_lshl_add_u64 v[198:199], s[4:5], 0, v[194:195]
	s_mov_b64 s[98:99], s[4:5]
	s_waitcnt vmcnt(5)
	ds_write_b128 v215, v[148:151]
	s_waitcnt vmcnt(4)
	ds_write_b128 v215, v[152:155] offset:8192
	s_waitcnt vmcnt(3)
	ds_write_b128 v216, v[16:19]
	s_waitcnt vmcnt(2)
	ds_write_b128 v217, v[20:23]
	s_waitcnt vmcnt(1)
	ds_write_b128 v216, v[24:27] offset:16384
	s_waitcnt vmcnt(0)
	ds_write_b128 v217, v[28:31] offset:16384
	s_cmp_lg_u32 s91, 0
	s_cselect_b64 s[50:51], -1, 0
	s_cmp_eq_u32 s91, 0
	s_cbranch_scc1 .LBB0_348
	s_and_b64 s[4:5], s[46:47], exec
	s_cselect_b32 s4, 0x8000, s7
	s_mov_b32 s5, s39
	v_lshl_add_u64 v[16:17], v[198:199], 0, s[4:5]
	v_add_co_u32_e32 v18, vcc, 0x2000, v16
	s_nop 1
	v_addc_co_u32_e32 v19, vcc, 0, v17, vcc
	global_load_dwordx4 v[148:151], v[16:17], off
	global_load_dwordx4 v[152:155], v[18:19], off

.LBB0_367:
	s_waitcnt vmcnt(0) lgkmcnt(0)
	s_barrier
	s_add_i32 s53, s53, -2
	s_add_i32 s87, s87, 2
	s_cmp_gt_u32 s88, s85
	s_cbranch_scc1 .LBB0_404
.LBB0_368:
	s_add_i32 s90, s87, -3
	s_cmp_gt_u32 s90, s84
	s_cbranch_scc1 .Ld0_h1_noK
	s_add_i32 s90, s87, -2
	s_cmp_lg_u64 s[46:47], 0
	s_cselect_b32 s90, s90, s53
	s_lshl_b32 s90, s90, 14
	s_add_u32 s92, s98, s90
	s_addc_u32 s93, s99, 0
	s_add_i32 m0, s100, 0x14000
	s_nop 0
	global_load_lds_dwordx4 v250, s[92:93]
	s_add_u32 s92, s92, 0x2000
	s_addc_u32 s93, s93, 0
	s_add_i32 m0, s100, 0x16000
	s_nop 0
	global_load_lds_dwordx4 v250, s[92:93]
.Ld0_h1_noK:
	s_add_i32 s90, s87, -3
	s_add_i32 s91, s53, 1
	s_cmp_lg_u64 s[46:47], 0
	s_cselect_b32 s90, s90, s91
	s_lshl_b32 s90, s90, 14
	s_add_u32 s92, s8, s90
	s_addc_u32 s93, s9, 0
	s_mov_b32 m0, s100
	s_nop 0
	global_load_lds_dwordx4 v251, s[92:93]
	s_add_u32 s92, s92, 0x2000
	s_addc_u32 s93, s93, 0
	s_add_i32 m0, s100, 0x2000
	s_nop 0
	global_load_lds_dwordx4 v251, s[92:93]
	s_add_u32 s92, s12, s90
	s_addc_u32 s93, s13, 0
	s_add_i32 m0, s100, 0x4000
	s_nop 0
	global_load_lds_dwordx4 v251, s[92:93]
	s_add_u32 s92, s92, 0x2000
	s_addc_u32 s93, s93, 0
	s_add_i32 m0, s100, 0x6000
	s_nop 0
	global_load_lds_dwordx4 v251, s[92:93]
	ds_read_b32 v65, v197 offset:1024
	v_max_f32_e32 v64, v64, v64
	v_mov_b32_e32 v229, 1.0
	s_waitcnt lgkmcnt(0)
	v_max_f32_e32 v65, v65, v65
	v_max_f32_e32 v64, v64, v65
	v_sub_f32_e32 v65, v64, v218
	v_mul_f32_e32 v65, 0x3db504f3, v65
	v_cmp_ge_f32_e32 vcc, s72, v65
	s_cmp_eq_u64 vcc, exec
	s_cbranch_scc0 .LBB0_402

.Lm0_h1B_nm:
	v_max3_f32 v0, v128, v129, v130
	v_max3_f32 v17, v131, v132, v133
	v_max3_f32 v18, v134, v135, v136
	v_max3_f32 v19, v137, v138, v139
	v_mfma_f32_32x32x16_bf16 v[80:95], v[172:175], v[104:107], v[80:95]
	v_max3_f32 v20, v140, v141, v142
	v_max3_f32 v0, v0, v17, v143
	v_max3_f32 v18, v18, v19, v20
	v_max_f32_e32 v0, v0, v18
	v_mov_b32_e32 v17, v0
	s_nop 1
	v_permlane32_swap_b32_e32 v0, v17
	v_max_f32_e32 v0, v0, v17
	v_mfma_f32_32x32x16_bf16 v[80:95], v[176:179], v[108:111], v[80:95]
	s_waitcnt lgkmcnt(0)
	v_mfma_f32_32x32x16_bf16 v[96:111], v[184:187], v[112:115], v[32:47]
	ds_read_b64_tr_b16 v[230:231], v194 offset:0xc600
	ds_read_b64_tr_b16 v[232:233], v194 offset:0xce00
	ds_read_b64_tr_b16 v[234:235], v194 offset:0xd600
	ds_read_b64_tr_b16 v[236:237], v194 offset:0xde00
	ds_read_b64_tr_b16 v[238:239], v194 offset:0xe600
	ds_read_b64_tr_b16 v[240:241], v194 offset:0xee00
	ds_read_b64_tr_b16 v[242:243], v194 offset:0xf600
	s_and_saveexec_b64 s[4:5], s[2:3]
	ds_write_b32 v226, v0
	s_or_b64 exec, exec, s[4:5]
	s_add_i32 s88, s87, -1
	s_add_i32 s89, s87, -2
	v_mfma_f32_32x32x16_bf16 v[96:111], v[180:183], v[116:119], v[96:111]
	ds_read_b64_tr_b16 v[244:245], v194 offset:0xfe00
	v_mfma_f32_32x32x16_bf16 v[96:111], v[172:175], v[120:123], v[96:111]
	v_mfma_f32_32x32x16_bf16 v[96:111], v[176:179], v[124:127], v[96:111]
	s_waitcnt lgkmcnt(0)
	v_mfma_f32_32x32x16_bf16 v[112:127], v[184:187], v[230:233], v[48:63]
	v_mul_f32_e32 v17, 0xbe0293ee, v218
	v_fmamk_f32 v16, v128, 0x3e0293ee, v17
	v_fmamk_f32 v15, v129, 0x3e0293ee, v17
	v_fmamk_f32 v14, v130, 0x3e0293ee, v17
	v_fmamk_f32 v13, v131, 0x3e0293ee, v17
	v_exp_f32_e32 v16, v16
	v_exp_f32_e32 v15, v15
	v_exp_f32_e32 v14, v14
	v_exp_f32_e32 v13, v13
	v_mfma_f32_32x32x16_bf16 v[112:127], v[180:183], v[234:237], v[112:127]
	v_fmamk_f32 v12, v132, 0x3e0293ee, v17
	v_fmamk_f32 v11, v133, 0x3e0293ee, v17
	v_fmamk_f32 v10, v134, 0x3e0293ee, v17
	v_fmamk_f32 v9, v135, 0x3e0293ee, v17
	v_exp_f32_e32 v12, v12
	v_exp_f32_e32 v11, v11
	v_exp_f32_e32 v10, v10
	v_exp_f32_e32 v9, v9
	v_mfma_f32_32x32x16_bf16 v[112:127], v[172:175], v[238:241], v[112:127]
	v_fmamk_f32 v8, v136, 0x3e0293ee, v17
	v_fmamk_f32 v7, v137, 0x3e0293ee, v17
	v_fmamk_f32 v6, v138, 0x3e0293ee, v17
	v_fmamk_f32 v5, v139, 0x3e0293ee, v17
	v_exp_f32_e32 v8, v8
	v_exp_f32_e32 v7, v7
	v_exp_f32_e32 v6, v6
	v_exp_f32_e32 v5, v5
	v_mfma_f32_32x32x16_bf16 v[112:127], v[176:179], v[242:245], v[112:127]
	v_fmamk_f32 v4, v140, 0x3e0293ee, v17
	v_fmamk_f32 v3, v141, 0x3e0293ee, v17
	v_fmamk_f32 v2, v142, 0x3e0293ee, v17
	v_fmac_f32_e32 v17, 0x3e0293ee, v143
	v_exp_f32_e32 v4, v4
	v_exp_f32_e32 v3, v3
	v_exp_f32_e32 v2, v2
	v_exp_f32_e32 v1, v17
	v_add_f32_e32 v17, v16, v15
	v_add_f32_e32 v18, v14, v13
	v_add_f32_e32 v17, v17, v18
	v_add_f32_e32 v18, v12, v11
	v_add_f32_e32 v19, v10, v9
	v_add_f32_e32 v18, v18, v19
	v_add_f32_e32 v17, v17, v18
	v_add_f32_e32 v18, v8, v7
	v_add_f32_e32 v19, v6, v5
	v_add_f32_e32 v18, v18, v19
	v_add_f32_e32 v19, v4, v3
	v_add_f32_e32 v20, v2, v1
	v_add_f32_e32 v19, v19, v20
	v_add_f32_e32 v18, v18, v19
	v_add_f32_e32 v231, v17, v18
	v_mov_b32_e32 v232, v231
	s_nop 1
	v_permlane32_swap_b32_e32 v231, v232
	v_cvt_pk_bf16_f32 v172, v16, v15
	v_cvt_pk_bf16_f32 v173, v14, v13
	v_cvt_pk_bf16_f32 v174, v12, v11
	v_cvt_pk_bf16_f32 v175, v10, v9
	v_cvt_pk_bf16_f32 v176, v8, v7
	v_cvt_pk_bf16_f32 v177, v6, v5
	v_cvt_pk_bf16_f32 v178, v4, v3
	v_cvt_pk_bf16_f32 v179, v2, v1
	s_nop 0
	v_permlane32_swap_b32_e32 v172, v174
	v_permlane32_swap_b32_e32 v173, v175
	v_permlane32_swap_b32_e32 v176, v178
	v_permlane32_swap_b32_e32 v177, v179
	ds_write_b128 v219, v[172:175]
	ds_write_b128 v219, v[176:179] offset:1024
	s_mov_b64 s[4:5], 0

.Lm0_h1A_nm:
	v_max3_f32 v0, v128, v129, v130
	v_max3_f32 v17, v131, v132, v133
	v_max3_f32 v18, v134, v135, v136
	v_max3_f32 v19, v137, v138, v139
	v_mfma_f32_32x32x16_bf16 v[80:95], v[184:187], v[104:107], v[80:95]
	v_max3_f32 v20, v140, v141, v142
	v_max3_f32 v0, v0, v17, v143
	v_max3_f32 v18, v18, v19, v20
	v_max_f32_e32 v0, v0, v18
	v_mov_b32_e32 v17, v0
	s_nop 1
	v_permlane32_swap_b32_e32 v0, v17
	v_max_f32_e32 v0, v0, v17
	v_mfma_f32_32x32x16_bf16 v[80:95], v[180:183], v[108:111], v[80:95]
	s_waitcnt lgkmcnt(0)
	v_mfma_f32_32x32x16_bf16 v[96:111], v[172:175], v[112:115], v[32:47]
	ds_read_b64_tr_b16 v[230:231], v194 offset:0x8600
	ds_read_b64_tr_b16 v[232:233], v194 offset:0x8e00
	ds_read_b64_tr_b16 v[234:235], v194 offset:0x9600
	ds_read_b64_tr_b16 v[236:237], v194 offset:0x9e00
	ds_read_b64_tr_b16 v[238:239], v194 offset:0xa600
	ds_read_b64_tr_b16 v[240:241], v194 offset:0xae00
	ds_read_b64_tr_b16 v[242:243], v194 offset:0xb600
	s_and_saveexec_b64 s[4:5], s[2:3]
	ds_write_b32 v226, v0
	s_or_b64 exec, exec, s[4:5]
	s_add_i32 s88, s87, -1
	s_add_i32 s89, s87, -2
	v_mfma_f32_32x32x16_bf16 v[96:111], v[176:179], v[116:119], v[96:111]
	ds_read_b64_tr_b16 v[244:245], v194 offset:0xbe00
	v_mfma_f32_32x32x16_bf16 v[96:111], v[184:187], v[120:123], v[96:111]
	v_mfma_f32_32x32x16_bf16 v[96:111], v[180:183], v[124:127], v[96:111]
	s_waitcnt lgkmcnt(0)
	v_mfma_f32_32x32x16_bf16 v[112:127], v[172:175], v[230:233], v[48:63]
	v_mul_f32_e32 v17, 0xbe0293ee, v218
	v_fmamk_f32 v16, v128, 0x3e0293ee, v17
	v_fmamk_f32 v15, v129, 0x3e0293ee, v17
	v_fmamk_f32 v14, v130, 0x3e0293ee, v17
	v_fmamk_f32 v13, v131, 0x3e0293ee, v17
	v_exp_f32_e32 v16, v16
	v_exp_f32_e32 v15, v15
	v_exp_f32_e32 v14, v14
	v_exp_f32_e32 v13, v13
	v_mfma_f32_32x32x16_bf16 v[112:127], v[176:179], v[234:237], v[112:127]
	v_fmamk_f32 v12, v132, 0x3e0293ee, v17
	v_fmamk_f32 v11, v133, 0x3e0293ee, v17
	v_fmamk_f32 v10, v134, 0x3e0293ee, v17
	v_fmamk_f32 v9, v135, 0x3e0293ee, v17
	v_exp_f32_e32 v12, v12
	v_exp_f32_e32 v11, v11
	v_exp_f32_e32 v10, v10
	v_exp_f32_e32 v9, v9
	v_mfma_f32_32x32x16_bf16 v[112:127], v[184:187], v[238:241], v[112:127]
	v_fmamk_f32 v8, v136, 0x3e0293ee, v17
	v_fmamk_f32 v7, v137, 0x3e0293ee, v17
	v_fmamk_f32 v6, v138, 0x3e0293ee, v17
	v_fmamk_f32 v5, v139, 0x3e0293ee, v17
	v_exp_f32_e32 v8, v8
	v_exp_f32_e32 v7, v7
	v_exp_f32_e32 v6, v6
	v_exp_f32_e32 v5, v5
	v_mfma_f32_32x32x16_bf16 v[112:127], v[180:183], v[242:245], v[112:127]
	v_fmamk_f32 v4, v140, 0x3e0293ee, v17
	v_fmamk_f32 v3, v141, 0x3e0293ee, v17
	v_fmamk_f32 v2, v142, 0x3e0293ee, v17
	v_fmac_f32_e32 v17, 0x3e0293ee, v143
	v_exp_f32_e32 v4, v4
	v_exp_f32_e32 v3, v3
	v_exp_f32_e32 v2, v2
	v_exp_f32_e32 v1, v17
	v_add_f32_e32 v17, v16, v15
	v_add_f32_e32 v18, v14, v13
	v_add_f32_e32 v17, v17, v18
	v_add_f32_e32 v18, v12, v11
	v_add_f32_e32 v19, v10, v9
	v_add_f32_e32 v18, v18, v19
	v_add_f32_e32 v17, v17, v18
	v_add_f32_e32 v18, v8, v7
	v_add_f32_e32 v19, v6, v5
	v_add_f32_e32 v18, v18, v19
	v_add_f32_e32 v19, v4, v3
	v_add_f32_e32 v20, v2, v1
	v_add_f32_e32 v19, v19, v20
	v_add_f32_e32 v18, v18, v19
	v_add_f32_e32 v231, v17, v18
	v_mov_b32_e32 v232, v231
	s_nop 1
	v_permlane32_swap_b32_e32 v231, v232
	v_cvt_pk_bf16_f32 v172, v16, v15
	v_cvt_pk_bf16_f32 v173, v14, v13
	v_cvt_pk_bf16_f32 v174, v12, v11
	v_cvt_pk_bf16_f32 v175, v10, v9
	v_cvt_pk_bf16_f32 v176, v8, v7
	v_cvt_pk_bf16_f32 v177, v6, v5
	v_cvt_pk_bf16_f32 v178, v4, v3
	v_cvt_pk_bf16_f32 v179, v2, v1
	s_nop 0
	v_permlane32_swap_b32_e32 v172, v174
	v_permlane32_swap_b32_e32 v173, v175
	v_permlane32_swap_b32_e32 v176, v178
	v_permlane32_swap_b32_e32 v177, v179
	ds_write_b128 v219, v[172:175]
	ds_write_b128 v219, v[176:179] offset:1024

.LBB0_377:
	s_waitcnt vmcnt(0) lgkmcnt(0)
	s_barrier
	s_add_i32 s90, s87, -1
	s_cmp_gt_u32 s90, s85
	s_cbranch_scc1 .Ld0_h2_noK
	s_add_i32 s91, s53, -1
	s_cmp_lg_u64 s[46:47], 0
	s_cselect_b32 s90, s90, s91
	s_lshl_b32 s90, s90, 14
	s_add_u32 s92, s98, s90
	s_addc_u32 s93, s99, 0
	s_add_i32 m0, s100, 0x10000
	s_nop 0
	global_load_lds_dwordx4 v250, s[92:93]
	s_add_u32 s92, s92, 0x2000
	s_addc_u32 s93, s93, 0
	s_add_i32 m0, s100, 0x12000
	s_nop 0
	global_load_lds_dwordx4 v250, s[92:93]
.Ld0_h2_noK:
	s_add_i32 s90, s87, -2
	s_cmp_lg_u64 s[46:47], 0
	s_cselect_b32 s90, s90, s53
	s_lshl_b32 s90, s90, 14
	s_add_u32 s92, s8, s90
	s_addc_u32 s93, s9, 0
	s_add_i32 m0, s100, 0x8000
	s_nop 0
	global_load_lds_dwordx4 v251, s[92:93]
	s_add_u32 s92, s92, 0x2000
	s_addc_u32 s93, s93, 0
	s_add_i32 m0, s100, 0xa000
	s_nop 0
	global_load_lds_dwordx4 v251, s[92:93]
	s_add_u32 s92, s12, s90
	s_addc_u32 s93, s13, 0
	s_add_i32 m0, s100, 0xc000
	s_nop 0
	global_load_lds_dwordx4 v251, s[92:93]
	s_add_u32 s92, s92, 0x2000
	s_addc_u32 s93, s93, 0
	s_add_i32 m0, s100, 0xe000
	s_nop 0
	global_load_lds_dwordx4 v251, s[92:93]
	ds_read_b32 v1, v197
	v_max_f32_e32 v0, v0, v0
	v_mov_b32_e32 v230, 1.0
	s_waitcnt lgkmcnt(0)
	v_max_f32_e32 v1, v1, v1
	v_max_f32_e32 v0, v0, v1
	v_sub_f32_e32 v1, v0, v218
	v_mul_f32_e32 v1, 0x3db504f3, v1
	v_cmp_ge_f32_e32 vcc, s72, v1
	s_cmp_eq_u64 vcc, exec
	s_cbranch_scc0 .LBB0_403

.Lm0_h2B_nm:
	v_max3_f32 v64, v128, v129, v130
	v_max3_f32 v81, v131, v132, v133
	v_max3_f32 v82, v134, v135, v136
	v_max3_f32 v83, v137, v138, v139
	v_mfma_f32_32x32x16_bf16 v[16:31], v[172:175], v[40:43], v[16:31]
	v_max3_f32 v84, v140, v141, v142
	v_max3_f32 v64, v64, v81, v143
	v_max3_f32 v82, v82, v83, v84
	v_max_f32_e32 v64, v64, v82
	v_mov_b32_e32 v81, v64
	s_nop 1
	v_permlane32_swap_b32_e32 v64, v81
	v_max_f32_e32 v64, v64, v81
	v_mfma_f32_32x32x16_bf16 v[16:31], v[176:179], v[44:47], v[16:31]
	s_waitcnt lgkmcnt(0)
	v_mfma_f32_32x32x16_bf16 v[32:47], v[184:187], v[48:51], v[96:111]
	ds_read_b64_tr_b16 v[234:235], v194 offset:0x4600
	ds_read_b64_tr_b16 v[236:237], v194 offset:0x4e00
	ds_read_b64_tr_b16 v[238:239], v194 offset:0x5600
	ds_read_b64_tr_b16 v[240:241], v194 offset:0x5e00
	ds_read_b64_tr_b16 v[242:243], v194 offset:0x6600
	ds_read_b64_tr_b16 v[244:245], v194 offset:0x6e00
	ds_read_b64_tr_b16 v[246:247], v194 offset:0x7600
	s_and_saveexec_b64 s[4:5], s[2:3]
	ds_write_b32 v226, v64 offset:1024
	s_or_b64 exec, exec, s[4:5]
	v_mfma_f32_32x32x16_bf16 v[32:47], v[180:183], v[52:55], v[32:47]
	ds_read_b64_tr_b16 v[248:249], v194 offset:0x7e00
	v_mfma_f32_32x32x16_bf16 v[32:47], v[172:175], v[56:59], v[32:47]
	v_mfma_f32_32x32x16_bf16 v[32:47], v[176:179], v[60:63], v[32:47]
	s_waitcnt lgkmcnt(0)
	v_mfma_f32_32x32x16_bf16 v[48:63], v[184:187], v[234:237], v[112:127]
	v_add_f32_e32 v90, v231, v232
	v_fmac_f32_e32 v90, v227, v229
	v_mul_f32_e32 v89, 0xbe0293ee, v218
	v_fmamk_f32 v80, v128, 0x3e0293ee, v89
	v_fmamk_f32 v79, v129, 0x3e0293ee, v89
	v_fmamk_f32 v78, v130, 0x3e0293ee, v89
	v_fmamk_f32 v77, v131, 0x3e0293ee, v89
	v_fmamk_f32 v72, v136, 0x3e0293ee, v89
	v_fmamk_f32 v71, v137, 0x3e0293ee, v89
	v_fmamk_f32 v70, v138, 0x3e0293ee, v89
	v_fmamk_f32 v69, v139, 0x3e0293ee, v89
	v_exp_f32_e32 v80, v80
	v_exp_f32_e32 v82, v79
	v_exp_f32_e32 v78, v78
	v_exp_f32_e32 v84, v77
	v_mfma_f32_32x32x16_bf16 v[48:63], v[180:183], v[238:241], v[48:63]
	v_fmamk_f32 v76, v132, 0x3e0293ee, v89
	v_fmamk_f32 v75, v133, 0x3e0293ee, v89
	v_fmamk_f32 v74, v134, 0x3e0293ee, v89
	v_fmamk_f32 v73, v135, 0x3e0293ee, v89
	v_exp_f32_e32 v81, v72
	v_exp_f32_e32 v83, v71
	v_exp_f32_e32 v79, v70
	v_exp_f32_e32 v85, v69
	v_mfma_f32_32x32x16_bf16 v[48:63], v[172:175], v[242:245], v[48:63]
	v_fmamk_f32 v68, v140, 0x3e0293ee, v89
	v_fmamk_f32 v67, v141, 0x3e0293ee, v89
	v_fmamk_f32 v66, v142, 0x3e0293ee, v89
	v_fmac_f32_e32 v89, 0x3e0293ee, v143
	v_exp_f32_e32 v76, v76
	v_exp_f32_e32 v86, v75
	v_exp_f32_e32 v74, v74
	v_exp_f32_e32 v88, v73
	v_mfma_f32_32x32x16_bf16 v[48:63], v[176:179], v[246:249], v[48:63]
	v_exp_f32_e32 v77, v68
	v_exp_f32_e32 v87, v67
	v_exp_f32_e32 v75, v66
	v_exp_f32_e32 v89, v89
	v_pk_add_f32 v[66:67], v[80:81], v[82:83]
	v_pk_add_f32 v[68:69], v[78:79], v[84:85]
	v_pk_add_f32 v[70:71], v[74:75], v[88:89]
	v_pk_add_f32 v[66:67], v[66:67], v[68:69]
	v_pk_add_f32 v[68:69], v[76:77], v[86:87]
	s_nop 0
	v_pk_add_f32 v[68:69], v[68:69], v[70:71]
	s_nop 0
	v_pk_add_f32 v[66:67], v[66:67], v[68:69]
	s_nop 0
	v_pk_add_f32 v[66:67], v[66:67], v[66:67] op_sel:[0,1] op_sel_hi:[1,0]
	s_nop 0
	v_mov_b32_e32 v65, v66
	s_nop 1
	v_permlane32_swap_b32_e32 v66, v65
	v_add_f32_e32 v227, v66, v65
	v_fmac_f32_e32 v227, v90, v230
	v_cvt_pk_bf16_f32 v172, v80, v82
	v_cvt_pk_bf16_f32 v173, v78, v84
	v_cvt_pk_bf16_f32 v174, v76, v86
	v_cvt_pk_bf16_f32 v175, v74, v88
	v_cvt_pk_bf16_f32 v176, v81, v83
	v_cvt_pk_bf16_f32 v177, v79, v85
	v_cvt_pk_bf16_f32 v178, v77, v87
	v_cvt_pk_bf16_f32 v179, v75, v89
	s_nop 0
	v_permlane32_swap_b32_e32 v172, v174
	v_permlane32_swap_b32_e32 v173, v175
	v_permlane32_swap_b32_e32 v176, v178
	v_permlane32_swap_b32_e32 v177, v179
	ds_write_b128 v219, v[172:175] offset:16384
	ds_write_b128 v219, v[176:179] offset:17408
	s_mov_b64 s[4:5], 0

.Lm0_h2A_nm:
	v_max3_f32 v64, v128, v129, v130
	v_max3_f32 v81, v131, v132, v133
	v_max3_f32 v82, v134, v135, v136
	v_max3_f32 v83, v137, v138, v139
	v_mfma_f32_32x32x16_bf16 v[16:31], v[184:187], v[40:43], v[16:31]
	v_max3_f32 v84, v140, v141, v142
	v_max3_f32 v64, v64, v81, v143
	v_max3_f32 v82, v82, v83, v84
	v_max_f32_e32 v64, v64, v82
	v_mov_b32_e32 v81, v64
	s_nop 1
	v_permlane32_swap_b32_e32 v64, v81
	v_max_f32_e32 v64, v64, v81
	v_mfma_f32_32x32x16_bf16 v[16:31], v[180:183], v[44:47], v[16:31]
	s_waitcnt lgkmcnt(0)
	v_mfma_f32_32x32x16_bf16 v[32:47], v[172:175], v[48:51], v[96:111]
	ds_read_b64_tr_b16 v[234:235], v194 offset:0x600
	ds_read_b64_tr_b16 v[236:237], v194 offset:0xe00
	ds_read_b64_tr_b16 v[238:239], v194 offset:0x1600
	ds_read_b64_tr_b16 v[240:241], v194 offset:0x1e00
	ds_read_b64_tr_b16 v[242:243], v194 offset:0x2600
	ds_read_b64_tr_b16 v[244:245], v194 offset:0x2e00
	ds_read_b64_tr_b16 v[246:247], v194 offset:0x3600
	s_and_saveexec_b64 s[4:5], s[2:3]
	ds_write_b32 v226, v64 offset:1024
	s_or_b64 exec, exec, s[4:5]
	v_mfma_f32_32x32x16_bf16 v[32:47], v[176:179], v[52:55], v[32:47]
	ds_read_b64_tr_b16 v[248:249], v194 offset:0x3e00
	v_mfma_f32_32x32x16_bf16 v[32:47], v[184:187], v[56:59], v[32:47]
	v_mfma_f32_32x32x16_bf16 v[32:47], v[180:183], v[60:63], v[32:47]
	s_waitcnt lgkmcnt(0)
	v_mfma_f32_32x32x16_bf16 v[48:63], v[172:175], v[234:237], v[112:127]
	v_add_f32_e32 v90, v231, v232
	v_fmac_f32_e32 v90, v227, v229
	v_mul_f32_e32 v89, 0xbe0293ee, v218
	v_fmamk_f32 v80, v128, 0x3e0293ee, v89
	v_fmamk_f32 v79, v129, 0x3e0293ee, v89
	v_fmamk_f32 v78, v130, 0x3e0293ee, v89
	v_fmamk_f32 v77, v131, 0x3e0293ee, v89
	v_fmamk_f32 v72, v136, 0x3e0293ee, v89
	v_fmamk_f32 v71, v137, 0x3e0293ee, v89
	v_fmamk_f32 v70, v138, 0x3e0293ee, v89
	v_fmamk_f32 v69, v139, 0x3e0293ee, v89
	v_exp_f32_e32 v80, v80
	v_exp_f32_e32 v82, v79
	v_exp_f32_e32 v78, v78
	v_exp_f32_e32 v84, v77
	v_mfma_f32_32x32x16_bf16 v[48:63], v[176:179], v[238:241], v[48:63]
	v_fmamk_f32 v76, v132, 0x3e0293ee, v89
	v_fmamk_f32 v75, v133, 0x3e0293ee, v89
	v_fmamk_f32 v74, v134, 0x3e0293ee, v89
	v_fmamk_f32 v73, v135, 0x3e0293ee, v89
	v_exp_f32_e32 v81, v72
	v_exp_f32_e32 v83, v71
	v_exp_f32_e32 v79, v70
	v_exp_f32_e32 v85, v69
	v_mfma_f32_32x32x16_bf16 v[48:63], v[184:187], v[242:245], v[48:63]
	v_fmamk_f32 v68, v140, 0x3e0293ee, v89
	v_fmamk_f32 v67, v141, 0x3e0293ee, v89
	v_fmamk_f32 v66, v142, 0x3e0293ee, v89
	v_fmac_f32_e32 v89, 0x3e0293ee, v143
	v_exp_f32_e32 v76, v76
	v_exp_f32_e32 v86, v75
	v_exp_f32_e32 v74, v74
	v_exp_f32_e32 v88, v73
	v_mfma_f32_32x32x16_bf16 v[48:63], v[180:183], v[246:249], v[48:63]
	v_exp_f32_e32 v77, v68
	v_exp_f32_e32 v87, v67
	v_exp_f32_e32 v75, v66
	v_exp_f32_e32 v89, v89
	v_pk_add_f32 v[66:67], v[80:81], v[82:83]
	v_pk_add_f32 v[68:69], v[78:79], v[84:85]
	v_pk_add_f32 v[70:71], v[74:75], v[88:89]
	v_pk_add_f32 v[66:67], v[66:67], v[68:69]
	v_pk_add_f32 v[68:69], v[76:77], v[86:87]
	s_nop 0
	v_pk_add_f32 v[68:69], v[68:69], v[70:71]
	s_nop 0
	v_pk_add_f32 v[66:67], v[66:67], v[68:69]
	s_nop 0
	v_pk_add_f32 v[66:67], v[66:67], v[66:67] op_sel:[0,1] op_sel_hi:[1,0]
	s_nop 0
	v_mov_b32_e32 v65, v66
	s_nop 1
	v_permlane32_swap_b32_e32 v66, v65
	v_add_f32_e32 v227, v66, v65
	v_fmac_f32_e32 v227, v90, v230
	v_cvt_pk_bf16_f32 v172, v80, v82
	v_cvt_pk_bf16_f32 v173, v78, v84
	v_cvt_pk_bf16_f32 v174, v76, v86
	v_cvt_pk_bf16_f32 v175, v74, v88
	v_cvt_pk_bf16_f32 v176, v81, v83
	v_cvt_pk_bf16_f32 v177, v79, v85
	v_cvt_pk_bf16_f32 v178, v77, v87
	v_cvt_pk_bf16_f32 v179, v75, v89
	s_nop 0
	v_permlane32_swap_b32_e32 v172, v174
	v_permlane32_swap_b32_e32 v173, v175
	v_permlane32_swap_b32_e32 v176, v178
	v_permlane32_swap_b32_e32 v177, v179
	ds_write_b128 v219, v[172:175] offset:16384
	ds_write_b128 v219, v[176:179] offset:17408

; __global__ void __launch_bounds__(NWAVES * 64, 2) mega_fwd(Args a) {
;     extern __shared__ __attribute__((aligned(16))) unsigned char lds[];
	.amdhsa_kernel _Z8mega_fwd4Args
		.amdhsa_group_segment_fixed_size 0
		.amdhsa_private_segment_fixed_size 0
		.amdhsa_kernarg_size 472
		.amdhsa_user_sgpr_count 2
		.amdhsa_user_sgpr_dispatch_ptr 0
		.amdhsa_user_sgpr_queue_ptr 0
		.amdhsa_user_sgpr_kernarg_segment_ptr 1
		.amdhsa_user_sgpr_dispatch_id 0
		.amdhsa_user_sgpr_kernarg_preload_length 0
		.amdhsa_user_sgpr_kernarg_preload_offset 0
		.amdhsa_user_sgpr_private_segment_size 0
		.amdhsa_uses_dynamic_stack 0
		.amdhsa_enable_private_segment 0
		.amdhsa_system_sgpr_workgroup_id_x 1
		.amdhsa_system_sgpr_workgroup_id_y 0
		.amdhsa_system_sgpr_workgroup_id_z 0
		.amdhsa_system_sgpr_workgroup_info 0
		.amdhsa_system_vgpr_workitem_id 2
		.amdhsa_next_free_vgpr 256
		.amdhsa_next_free_sgpr 102
		.amdhsa_accum_offset 256
		.amdhsa_reserve_vcc 1
		.amdhsa_float_round_mode_32 0
		.amdhsa_float_round_mode_16_64 0
		.amdhsa_float_denorm_mode_32 3
		.amdhsa_float_denorm_mode_16_64 3
		.amdhsa_dx10_clamp 1
		.amdhsa_ieee_mode 1
		.amdhsa_fp16_overflow 0
		.amdhsa_tg_split 0
		.amdhsa_exception_fp_ieee_invalid_op 0
		.amdhsa_exception_fp_denorm_src 0
		.amdhsa_exception_fp_ieee_div_zero 0
		.amdhsa_exception_fp_ieee_overflow 0
		.amdhsa_exception_fp_ieee_underflow 0
		.amdhsa_exception_fp_ieee_inexact 0
		.amdhsa_exception_int_div_zero 0
	.end_amdhsa_kernel
